# v25 + RWKV lora GEMM runs only the one 128-wide K block whose weights are non-zero for its column segment (others are structurally zero)
# speedup vs baseline: 1.0057x; 1.0057x over previous
;     DI bool next(int i, Unit& u) const { if (!so.next(i, u)) return false; u.ak = (u.pn >= 4) ? 256 : 0; return true; }
;     DI bool next(int i, Unit& u) const { if (!so.next(i >> 2, u)) return false; u.sub = i & 3; u.ak = u.sub * 512; u.brow = u.sub * D + u.pn * BM; return true; }
; #define PG8_STAGE(bufoff, gbase, voff) do { _Pragma("unroll") for (int _i = 0; _i < 2; ++_i) \
;         __builtin_amdgcn_global_load_lds((const unsigned*)((const char*)(gbase) + (voff)[_i]), (LAS unsigned*)(lds + (bufoff) + ldsw + _i * 8192), 16, 0, 0); } while (0)
; #define PG8_WAIT_V(n) asm volatile("s_waitcnt vmcnt(" #n ")" ::: "memory")
; #define PG8_BAR __builtin_amdgcn_s_barrier()
;     DI bool next(int i, Unit& u) const {
;         const long L = (long)i * G + c; if (L >= nwg) return false;
;         int wgid = (int)L; { const int q = nwg / NXCD, r = nwg % NXCD, xcd = wgid % NXCD, off = wgid / NXCD; wgid = (xcd < r ? xcd * (q + 1) : r * (q + 1) + (xcd - r) * q) + off; }
;         const int nig = WGM * nN, gid = wgid / nig, fm = gid * WGM, gsz = (nM - fm) < WGM ? (nM - fm) : WGM;
;         u.pm = fm + ((wgid % nig) % gsz); u.pn = (wgid % nig) / gsz; u.ak = 0; u.brow = u.pn * BM; u.sub = 0; return true;
; template <class Epi, class Sched, bool ALIGN_EPI>
; DI void gemm_phase(LAS unsigned char* lds, const Gemm g, const Sched& Sc, const Epi& E, const int tid) {
;     ...
;     const char* cA = (const char*)g.A + ((size_t)cur.pm * BM * g.lda + cur.ak) * 2; const char* cB = (const char*)g.Bt + (size_t)cur.brow * g.ldb * 2;
;     PG8_STAGE(PG8_SB(0, 0), cB, voffB); PG8_STAGE(PG8_SB(0, 1), cB + hB, voffB); PG8_STAGE(PG8_SA(0, 0), cA, voffA); PG8_STAGE(PG8_SA(0, 1), cA + hA, voffA);
;     if (wr == 1) PG8_BAR;
;     PG8_WAIT_V(2); PG8_BAR;
;     PG8_STAGE(PG8_SB(1, 0), cB + kstep, voffB); PG8_STAGE(PG8_SA(1, 0), cA + kstep, voffA); PG8_STAGE(PG8_SB(1, 1), cB + hB + kstep, voffB);
;     PG8_WAIT_V(6); PG8_BAR;
.LBB0_985:
	s_andn2_b64 vcc, exec, s[2:3]
	s_cbranch_vccnz .LBB0_1066
	v_readlane_b32 s2, v235, 35
	v_readlane_b32 s3, v235, 36
	s_and_b64 s[2:3], s[2:3], exec
	s_cselect_b32 s12, 6, 8
	s_lshl_b32 s20, s12, 5
	v_mov_b32_e32 v16, v0
	s_mov_b64 s[40:41], s[86:87]
	s_mov_b32 s2, s21
	v_readlane_b32 s56, v253, 0
	s_cmp_ge_i32 s56, s20
	v_readfirstlane_b32 s3, v16
	s_cbranch_scc1 .LBB0_1016
	v_lshlrev_b32_e32 v2, 4, v16
	v_add_u32_e32 v3, 0x2000, v2
	v_ashrrev_i32_e32 v4, 31, v3
	v_lshrrev_b32_e32 v4, 22, v4
	v_add_u32_e32 v4, v3, v4
	v_ashrrev_i32_e32 v10, 10, v4
	v_mul_i32_i24_e32 v4, 0x400, v10
	v_sub_u32_e32 v3, v3, v4
	v_lshrrev_b32_e32 v4, 4, v3
	v_bitop3_b32 v3, v4, v3, 32 bitop3:0x6c
	v_ashrrev_i32_e32 v4, 31, v3
	v_lshrrev_b32_e32 v4, 26, v4
	v_add_u32_e32 v4, v3, v4
	v_lshlrev_b32_e32 v5, 3, v10
	v_ashrrev_i32_e32 v11, 6, v4
	v_and_b32_e32 v5, -16, v5
	v_add_u32_e32 v5, v11, v5
	v_and_b32_e32 v6, 3, v11
	s_mov_b32 s13, 0x3fffe0
	v_lshrrev_b32_e32 v7, 2, v5
	v_lshlrev_b32_e32 v8, 1, v5
	v_and_b32_e32 v4, 0xc0, v4
	v_and_or_b32 v6, v5, s13, v6
	v_and_b32_e32 v7, 4, v7
	v_and_b32_e32 v8, 24, v8
	v_sub_u32_e32 v3, v3, v4
	v_or3_b32 v6, v6, v7, v8
	v_lshlrev_b32_e32 v7, 5, v10
	v_ashrrev_i16_sdwa v3, v239, sext(v3) dst_sel:DWORD dst_unused:UNUSED_PAD src0_sel:DWORD src1_sel:BYTE_0
	v_and_b32_e32 v7, 32, v7
	v_bfe_i32 v12, v3, 0, 16
	v_add_lshl_u32 v3, v7, v12, 1
	s_waitcnt vmcnt(0)
	v_lshl_add_u32 v180, v6, 10, v3
	v_lshl_add_u32 v182, v5, 10, v3
	v_bfe_i32 v3, v16, 27, 1
	v_lshrrev_b32_e32 v3, 22, v3
	v_readlane_b32 s26, v235, 32
	v_add_u32_e32 v3, v2, v3
	v_readlane_b32 s27, v235, 33
	v_and_b32_e32 v3, 0xfffffc00, v3
	s_mov_b32 s27, s21
	s_lshl_b32 s57, s12, 2
	v_sub_u32_e32 v2, v2, v3
	s_lshl_b64 s[8:9], s[26:27], 21
	s_or_b32 s17, s57, 1
	s_lshl_b32 s67, s12, 3
	v_lshrrev_b32_e32 v3, 4, v2
	v_ashrrev_i32_e32 v4, 31, v16
	s_add_u32 s68, s40, 0x48000000
	v_bitop3_b32 v2, v3, v2, 32 bitop3:0x6c
	v_lshrrev_b32_e32 v4, 26, v4
	s_addc_u32 s69, s41, 0
	v_ashrrev_i32_e32 v3, 31, v2
	v_add_u32_e32 v4, v16, v4
	s_add_u32 s8, s40, s8
	v_lshrrev_b32_e32 v3, 26, v3
	v_ashrrev_i32_e32 v14, 6, v4
	s_addc_u32 s9, s41, s9
	v_add_u32_e32 v3, v2, v3
	v_lshlrev_b32_e32 v4, 3, v14
	s_add_u32 s70, s8, 0xf300000
	v_ashrrev_i32_e32 v13, 6, v3
	v_and_b32_e32 v4, -16, v4
	s_addc_u32 s71, s9, 0
	v_add_u32_e32 v4, v13, v4
	v_and_b32_e32 v5, 3, v13
	s_ashr_i32 s72, s56, 31
	v_and_or_b32 v5, v4, s13, v5
	s_lshr_b32 s13, s72, 29
	s_add_i32 s13, s56, s13
	s_ashr_i32 s9, s3, 6
	s_ashr_i32 s16, s13, 3
	s_and_b32 s13, s13, -8
	s_ashr_i32 s11, s3, 8
	s_lshl_b32 s8, s9, 10
	s_sub_i32 s13, s56, s13
	s_cmp_lt_i32 s13, 0
	v_lshrrev_b32_e32 v6, 2, v4
	v_lshlrev_b32_e32 v7, 1, v4
	v_and_b32_e32 v3, 0xc0, v3
	v_writelane_b32 v235, s17, 37
	s_cselect_b32 s17, s17, s57
	s_abs_i32 s73, s67
	v_and_b32_e32 v6, 4, v6
	v_and_b32_e32 v7, 24, v7
	v_sub_u32_e32 v2, v2, v3
	v_cvt_f32_u32_e32 v3, s73
	v_or3_b32 v5, v5, v6, v7
	v_lshlrev_b32_e32 v6, 5, v14
	v_ashrrev_i16_sdwa v2, v239, sext(v2) dst_sel:DWORD dst_unused:UNUSED_PAD src0_sel:DWORD src1_sel:BYTE_0
	v_and_b32_e32 v6, 32, v6
	v_bfe_i32 v15, v2, 0, 16
	v_add_lshl_u32 v2, v6, v15, 1
	v_lshl_add_u32 v184, v5, 10, v2
	v_lshl_add_u32 v186, v4, 10, v2
	v_rcp_iflag_f32_e32 v2, v3
	s_mul_i32 s13, s13, s17
	s_sub_i32 s17, 0, s73
	s_add_i32 s13, s13, s16
	v_mul_f32_e32 v2, 0x4f7ffffe, v2
	v_cvt_u32_f32_e32 v2, v2
	s_ashr_i32 s16, s13, 31
	s_bfe_i32 s12, s12, 0x1001c
	v_writelane_b32 v235, s12, 39
	v_readfirstlane_b32 s18, v2
	s_mul_i32 s17, s17, s18
	s_mul_hi_u32 s17, s18, s17
	s_xor_b32 s12, s16, s12
	s_abs_i32 s16, s13
	s_add_i32 s17, s18, s17
	v_writelane_b32 v235, s17, 40
	s_mul_hi_u32 s17, s16, s17
	s_mul_i32 s18, s17, s73
	s_sub_i32 s16, s16, s18
	s_add_i32 s18, s17, 1
	s_sub_i32 s19, s16, s73
	s_cmp_ge_u32 s16, s73
	s_cselect_b32 s17, s18, s17
	s_cselect_b32 s16, s19, s16
	s_add_i32 s18, s17, 1
	s_cmp_ge_u32 s16, s73
	s_cselect_b32 s16, s18, s17
	s_xor_b32 s16, s16, s12
	s_sub_i32 s12, s16, s12
	s_lshl_b32 s16, s12, 3
	s_sub_i32 s17, 32, s16
	s_min_i32 s17, s17, 8
	v_cvt_f32_i32_e32 v2, s17
	s_mul_i32 s12, s12, s67
	s_sub_i32 s18, s13, s12
	v_cvt_f32_i32_e32 v3, s18
	v_rcp_iflag_f32_e32 v4, v2
	s_xor_b32 s12, s18, s17
	s_ashr_i32 s12, s12, 30
	s_or_b32 s19, s12, 1
	v_mul_f32_e32 v4, v3, v4
	v_trunc_f32_e32 v4, v4
	v_fma_f32 v3, -v4, v2, v3
	v_cvt_i32_f32_e32 v4, v4
	v_cmp_ge_f32_e64 s[12:13], |v3|, |v2|
	s_and_b64 s[12:13], s[12:13], exec
	s_cselect_b32 s12, s19, 0
	v_readfirstlane_b32 s13, v4
	s_add_i32 s12, s13, s12
	s_sext_i32_i8 s24, s12
	s_mul_i32 s12, s12, s17
	s_sub_i32 s12, s18, s12
	s_sext_i32_i8 s12, s12
	s_add_i32 s12, s16, s12
	s_lshl_b32 s16, s24, 8
	s_ashr_i32 s17, s16, 31
	s_ashr_i32 s13, s12, 31
	s_lshl_b64 s[16:17], s[16:17], 10
	s_lshl_b64 s[22:23], s[12:13], 18
	s_add_u32 s18, s70, s16
	s_addc_u32 s19, s71, s17
	s_andn2_b32 vcc_lo, s24, 1
	s_lshl_b32 vcc_lo, vcc_lo, 7
	s_add_u32 s18, s18, vcc_lo
	s_addc_u32 s19, s19, 0
	s_add_i32 s76, s2, 0x10000
	s_add_i32 s77, s76, s8
	s_add_i32 s78, s77, 0x2000
	s_add_u32 s16, s18, 0x20000
	s_addc_u32 s17, s19, 0
	s_add_i32 s79, s2, 0x14000
	s_add_i32 s80, s79, s8
	s_mov_b32 m0, s77
	s_add_i32 s81, s80, 0x2000
	global_load_lds_dwordx4 v184, s[18:19]
	s_mov_b32 m0, s78
	s_add_u32 s22, s68, s22
	global_load_lds_dwordx4 v180, s[18:19]
	s_mov_b32 m0, s80
	s_addc_u32 s23, s69, s23
	s_add_u32 s22, s22, vcc_lo
	s_addc_u32 s23, s23, 0
	s_add_i32 s82, s2, s8
	global_load_lds_dwordx4 v184, s[16:17]
	s_mov_b32 m0, s81
	s_add_i32 s83, s82, 0x2000
	global_load_lds_dwordx4 v180, s[16:17]
	s_mov_b32 m0, s82
	s_add_u32 s16, s22, 0x20000
	global_load_lds_dwordx4 v186, s[22:23]
	s_mov_b32 m0, s83
	s_addc_u32 s17, s23, 0
	s_add_i32 s84, s82, 0x4000
	global_load_lds_dwordx4 v182, s[22:23]
	s_mov_b32 m0, s84
	s_add_i32 s85, s82, 0x6000
	global_load_lds_dwordx4 v186, s[16:17]
	s_mov_b32 m0, s85
	s_cmp_eq_u32 s11, 1
	global_load_lds_dwordx4 v182, s[16:17]
	v_mov_b32_e32 v185, v19
	v_mov_b32_e32 v181, v19
	v_mov_b32_e32 v187, v19
	v_mov_b32_e32 v183, v19
	s_cselect_b64 s[16:17], -1, 0
	v_mov_b32_e32 v246, 1
	v_lshl_add_u64 v[6:7], s[18:19], 0, v[184:185]
	v_lshl_add_u64 v[4:5], s[18:19], 0, v[180:181]
	v_lshl_add_u64 v[2:3], s[22:23], 0, v[186:187]
	v_writelane_b32 v235, s16, 41
	s_cmp_lg_u32 s11, 1
	v_lshl_add_u64 v[8:9], s[22:23], 0, v[182:183]
	v_writelane_b32 v235, s17, 42
	s_cbranch_scc1 .LBB0_989
	s_barrier

; template <class Epi, class Sched, bool ALIGN_EPI>
; DI void gemm_phase(LAS unsigned char* lds, const Gemm g, const Sched& Sc, const Epi& E, const int tid) {
;     ...
;         const char* nA = has_next ? (const char*)g.A + ((size_t)nxt.pm * BM * g.lda + nxt.ak) * 2 : cA; const char* nB = has_next ? (const char*)g.Bt + (size_t)nxt.brow * g.ldb * 2 : cB;
;         for (int t = 0; t < nt; t += 2) {
;     ...
;         if (zero) {
; #pragma unroll
;         for (int a = 0; a < 2; ++a)
; #pragma unroll
;             for (int b = 0; b < 2; ++b)
; #pragma unroll
;                 for (int m = 0; m < 4; ++m)
; #pragma unroll
;                     for (int n = 0; n < 2; ++n) acc[a][b][m][n] = (f32x4){0.f, 0.f, 0.f, 0.f};
.LBB0_994:
	s_ashr_i32 s3, s2, 31
	s_lshl_b64 s[8:9], s[2:3], 18
	s_add_u32 s26, s68, s8
	s_addc_u32 s27, s69, s9
	s_and_b64 s[8:9], s[36:37], exec
	s_cselect_b32 s3, s27, s23
	s_cselect_b32 s13, s26, s22
	s_ashr_i32 s17, s16, 31
	s_lshl_b64 s[8:9], s[16:17], 10
	s_add_u32 s8, s70, s8
	s_addc_u32 s9, s71, s9
	s_and_b64 s[30:31], s[36:37], exec
	s_cselect_b32 s17, s9, s19
	s_cselect_b32 s25, s8, s18
	s_add_u32 s38, s18, 0x100
	s_addc_u32 s39, s19, 0
	s_add_u32 s18, s22, 0x20080
	v_mov_b32_e32 v2, 0
	s_addc_u32 s19, s23, 0
	s_mov_b32 s52, 4
	v_mov_b32_e32 v3, v2
	v_mov_b32_e32 v4, v2
	v_mov_b32_e32 v5, v2
	v_mov_b32_e32 v6, v2
	v_mov_b32_e32 v7, v2
	v_mov_b32_e32 v8, v2
	v_mov_b32_e32 v9, v2
	v_mov_b32_e32 v20, v2
	v_mov_b32_e32 v21, v2
	v_mov_b32_e32 v22, v2
	v_mov_b32_e32 v23, v2
	v_mov_b32_e32 v24, v2
	v_mov_b32_e32 v25, v2
	v_mov_b32_e32 v26, v2
	v_mov_b32_e32 v27, v2
	v_mov_b32_e32 v36, v2
	v_mov_b32_e32 v37, v2
	v_mov_b32_e32 v38, v2
	v_mov_b32_e32 v39, v2
	v_mov_b32_e32 v40, v2
	v_mov_b32_e32 v41, v2
	v_mov_b32_e32 v42, v2
	v_mov_b32_e32 v43, v2
	v_mov_b32_e32 v52, v2
	v_mov_b32_e32 v53, v2
	v_mov_b32_e32 v54, v2
	v_mov_b32_e32 v55, v2
	v_mov_b32_e32 v56, v2
	v_mov_b32_e32 v57, v2
	v_mov_b32_e32 v58, v2
	v_mov_b32_e32 v59, v2
	v_mov_b32_e32 v10, v2
	v_mov_b32_e32 v11, v2
	v_mov_b32_e32 v12, v2
	v_mov_b32_e32 v13, v2
	v_mov_b32_e32 v14, v2
	v_mov_b32_e32 v15, v2
	v_mov_b32_e32 v16, v2
	v_mov_b32_e32 v17, v2
	v_mov_b32_e32 v28, v2
	v_mov_b32_e32 v29, v2
	v_mov_b32_e32 v30, v2
	v_mov_b32_e32 v31, v2
	v_mov_b32_e32 v32, v2
	v_mov_b32_e32 v33, v2
	v_mov_b32_e32 v34, v2
	v_mov_b32_e32 v35, v2
	v_mov_b32_e32 v44, v2
	v_mov_b32_e32 v45, v2
	v_mov_b32_e32 v46, v2
	v_mov_b32_e32 v47, v2
	v_mov_b32_e32 v48, v2
	v_mov_b32_e32 v49, v2
	v_mov_b32_e32 v50, v2
	v_mov_b32_e32 v51, v2
	v_mov_b32_e32 v60, v2
	v_mov_b32_e32 v61, v2
	v_mov_b32_e32 v62, v2
	v_mov_b32_e32 v63, v2
	v_mov_b32_e32 v64, v2
	v_mov_b32_e32 v65, v2
	v_mov_b32_e32 v66, v2
	v_mov_b32_e32 v67, v2
	v_mov_b32_e32 v68, v2
	v_mov_b32_e32 v69, v2
	v_mov_b32_e32 v70, v2
	v_mov_b32_e32 v71, v2
	v_mov_b32_e32 v72, v2
	v_mov_b32_e32 v73, v2
	v_mov_b32_e32 v74, v2
	v_mov_b32_e32 v75, v2
	v_mov_b32_e32 v84, v2
	v_mov_b32_e32 v85, v2
	v_mov_b32_e32 v86, v2
	v_mov_b32_e32 v87, v2
	v_mov_b32_e32 v88, v2
	v_mov_b32_e32 v89, v2
	v_mov_b32_e32 v90, v2
	v_mov_b32_e32 v91, v2
	v_mov_b32_e32 v100, v2
	v_mov_b32_e32 v101, v2
	v_mov_b32_e32 v102, v2
	v_mov_b32_e32 v103, v2
	v_mov_b32_e32 v104, v2
	v_mov_b32_e32 v105, v2
	v_mov_b32_e32 v106, v2
	v_mov_b32_e32 v107, v2
	v_mov_b32_e32 v116, v2
	v_mov_b32_e32 v117, v2
	v_mov_b32_e32 v118, v2
	v_mov_b32_e32 v119, v2
	v_mov_b32_e32 v120, v2
	v_mov_b32_e32 v121, v2
	v_mov_b32_e32 v122, v2
	v_mov_b32_e32 v123, v2
	v_mov_b32_e32 v76, v2
	v_mov_b32_e32 v77, v2
	v_mov_b32_e32 v78, v2
	v_mov_b32_e32 v79, v2
	v_mov_b32_e32 v80, v2
	v_mov_b32_e32 v81, v2
	v_mov_b32_e32 v82, v2
	v_mov_b32_e32 v83, v2
	v_mov_b32_e32 v92, v2
	v_mov_b32_e32 v93, v2
	v_mov_b32_e32 v94, v2
	v_mov_b32_e32 v95, v2
	v_mov_b32_e32 v96, v2
	v_mov_b32_e32 v97, v2
	v_mov_b32_e32 v98, v2
	v_mov_b32_e32 v99, v2
	v_mov_b32_e32 v108, v2
	v_mov_b32_e32 v109, v2
	v_mov_b32_e32 v110, v2
	v_mov_b32_e32 v111, v2
	v_mov_b32_e32 v112, v2
	v_mov_b32_e32 v113, v2
	v_mov_b32_e32 v114, v2
	v_mov_b32_e32 v115, v2
	v_mov_b32_e32 v124, v2
	v_mov_b32_e32 v125, v2
	v_mov_b32_e32 v126, v2
	v_mov_b32_e32 v127, v2
	v_mov_b32_e32 v128, v2
	v_mov_b32_e32 v129, v2
	v_mov_b32_e32 v130, v2
	v_mov_b32_e32 v131, v2
